# on top of flip removal: one static s_setprio 1 for waves 4-7 at kernel entry
# baseline (speedup 1.0000x reference)
; #define LAS __attribute__((address_space(3)))
; __global__ void __launch_bounds__(512, 2) fwd_mega(Params p) {
;   extern __shared__ __attribute__((aligned(16))) unsigned char shm[];
;   cg::grid_group grid = cg::this_grid();
;   unsigned char* ws = p.ws; unsigned char* ob = (unsigned char*)p.out;
;   bf16_t* XN = (bf16_t*)(ws + WS_XN); bf16_t* DELTA = (bf16_t*)(ws + WS_DELTA);
;   volatile LAS unsigned* xst = (volatile LAS unsigned*)(LAS unsigned char*)(shm + LDS_BYTES - 16);
;   if (threadIdx.x == 0) { xst[0] = 0u; xst[1] = 0u; }
;   __syncthreads();
_Z8fwd_mega6Params:
	s_load_dwordx8 s[36:43], s[0:1], 0xe0
	s_load_dwordx8 s[4:11], s[0:1], 0xc0
	s_load_dwordx2 s[90:91], s[0:1], 0x100
	v_and_b32_e32 v196, 0x3ff, v0
	v_readfirstlane_b32 s98, v0
	s_bitcmp1_b32 s98, 8
	s_cbranch_scc0 .Lprio_done
	s_setprio 1
.Lprio_done:
	s_waitcnt lgkmcnt(0)
	v_writelane_b32 v251, s4, 0
	s_nop 1
	v_writelane_b32 v251, s5, 1
	v_writelane_b32 v251, s6, 2
	v_writelane_b32 v251, s7, 3
	v_writelane_b32 v251, s8, 4
	v_writelane_b32 v251, s9, 5
	v_writelane_b32 v251, s10, 6
	v_writelane_b32 v251, s11, 7
	s_add_u32 s4, s0, 0x100
	s_addc_u32 s5, s1, 0
	v_writelane_b32 v251, s4, 8
	s_nop 1
	v_writelane_b32 v251, s5, 9
	v_cmp_eq_u32_e64 s[4:5], 0, v196
	s_mov_b64 s[6:7], exec
	s_nop 0
	v_writelane_b32 v251, s4, 10
	s_nop 1
	v_writelane_b32 v251, s5, 11
	s_and_b64 s[4:5], s[6:7], s[4:5]
	s_mov_b64 exec, s[4:5]
	s_cbranch_execz .LBB0_2
	s_add_i32 s4, 0, 0x257f0
	v_mov_b32_e32 v1, 0
	v_mov_b32_e32 v2, s4
	s_add_i32 s4, 0, 0x257f4
	ds_write_b32 v2, v1
	v_mov_b32_e32 v2, s4
	ds_write_b32 v2, v1
